# projection epilogue: rope position loads batched behind one wait; xq epilogue: row-statistic loads hoisted and waited once
# speedup vs baseline: 1.0125x; 1.0005x over previous
;     __device__ __forceinline__ void operator()(const f32x4 (&acc)[2][2][4][2], const Unit& u, int wr, int wc, int fr, int fq) const {
;     ...
;         const int d0 = 8 * fq;
;         f32x4 g0a = {1.f, 1.f, 1.f, 1.f}, g0b = g0a, g1a = g0a, g1b = g0a;
;         if (mode == 2) { g0a = *(const f32x4*)(g + d0); g0b = *(const f32x4*)(g + d0 + 4); g1a = *(const f32x4*)(g + 32 + d0); g1b = *(const f32x4*)(g + 36 + d0); }
;         const float* sbp = sb + pn * 256 + wc * 32 + d0;
;         const f32x4 s0a = *(const f32x4*)sbp, s0b = *(const f32x4*)(sbp + 4), s1a = *(const f32x4*)(sbp + 128), s1b = *(const f32x4*)(sbp + 132);
;         const f32x4 fr0 = *(const f32x4*)(rft + d0), fr1 = *(const f32x4*)(rft + d0 + 4);
;         float pf[2][4], rr[2][4];
; #pragma unroll
;         for (int ai = 0; ai < 2; ++ai)
; #pragma unroll
;             for (int m = 0; m < 4; ++m) { const int row_ = u.pm * BM + ai * HALF + wr * 64 + m * 16 + fr; rr[ai][m] = rs[row_]; pf[ai][m] = mode == 2 ? (float)pos[row_] : 0.f; }
.LBB0_775:
	s_lshl_b32 s0, s75, 8
	s_ashr_i32 s1, s0, 31
	v_lshl_add_u64 v[16:17], s[0:1], 2, v[138:139]
	global_load_dwordx4 v[32:35], v[16:17], off offset:16
	global_load_dwordx4 v[36:39], v[16:17], off
	global_load_dwordx4 v[24:27], v[16:17], off offset:528
	global_load_dwordx4 v[28:31], v[16:17], off offset:512
	s_nop 0
	global_load_dwordx4 v[16:19], v[140:141], off offset:16
	global_load_dwordx4 v[20:23], v[140:141], off
	v_lshl_add_u32 v216, s29, 8, v151
	v_ashrrev_i32_e32 v217, 31, v216
	v_lshl_add_u64 v[72:73], v[216:217], 2, s[26:27]
	global_load_dword v94, v[72:73], off
	v_mov_b32_e32 v224, 0
	s_and_b64 vcc, exec, s[6:7]
	v_lshl_add_u64 v[218:219], v[216:217], 2, s[12:13]
	v_mov_b32_e32 v95, 0
	s_cbranch_vccnz .LBB0_777
	global_load_dword v95, v[218:219], off
.LBB0_777:
	v_or_b32_e32 v212, 16, v216
	v_ashrrev_i32_e32 v213, 31, v212
	v_lshl_add_u64 v[72:73], v[212:213], 2, s[26:27]
	global_load_dword v214, v[72:73], off
	s_and_b64 vcc, exec, s[6:7]
	s_cbranch_vccnz .LBB0_779
	global_load_dword v224, v[218:219], off offset:64
.LBB0_779:
	v_or_b32_e32 v192, 32, v216
	v_ashrrev_i32_e32 v193, 31, v192
	v_lshl_add_u64 v[72:73], v[192:193], 2, s[26:27]
	global_load_dword v210, v[72:73], off
	v_mov_b32_e32 v222, 0
	s_and_b64 vcc, exec, s[6:7]
	v_mov_b32_e32 v223, 0
	s_cbranch_vccnz .LBB0_781
	global_load_dword v223, v[218:219], off offset:128
.LBB0_781:
	v_or_b32_e32 v172, 48, v216
	v_ashrrev_i32_e32 v173, 31, v172
	v_lshl_add_u64 v[72:73], v[172:173], 2, s[26:27]
	global_load_dword v190, v[72:73], off
	s_and_b64 vcc, exec, s[6:7]
	s_cbranch_vccnz .LBB0_783
	global_load_dword v222, v[218:219], off offset:192
.LBB0_783:
	v_add_u32_e32 v152, 0x80, v216
	v_ashrrev_i32_e32 v153, 31, v152
	v_lshl_add_u64 v[72:73], v[152:153], 2, s[26:27]
	global_load_dword v170, v[72:73], off
	v_mov_b32_e32 v220, 0
	s_and_b64 vcc, exec, s[6:7]
	v_mov_b32_e32 v221, 0
	s_cbranch_vccnz .LBB0_785
	global_load_dword v221, v[218:219], off offset:512
.LBB0_785:
	v_add_u32_e32 v114, 0x90, v216
	v_ashrrev_i32_e32 v115, 31, v114
	v_lshl_add_u64 v[72:73], v[114:115], 2, s[26:27]
	global_load_dword v150, v[72:73], off
	s_and_b64 vcc, exec, s[6:7]
	s_cbranch_vccnz .LBB0_787
	global_load_dword v220, v[218:219], off offset:576
.LBB0_787:
	v_add_u32_e32 v92, 0xa0, v216
	v_ashrrev_i32_e32 v93, 31, v92
	v_lshl_add_u64 v[72:73], v[92:93], 2, s[26:27]
	global_load_dword v112, v[72:73], off
	v_mov_b32_e32 v91, 0
	s_and_b64 vcc, exec, s[6:7]
	v_mov_b32_e32 v113, 0
	s_cbranch_vccnz .LBB0_789
	global_load_dword v113, v[218:219], off offset:640

; __device__ __forceinline__ float sq4(const f32x4 v) { return (v[0] * v[0] + v[1] * v[1]) + (v[2] * v[2] + v[3] * v[3]); }
; __device__ __forceinline__ f32x4 cvti4(const f32x4 a) { typedef int i32x4_ __attribute__((ext_vector_type(4))); const i32x4_ i = __builtin_bit_cast(i32x4_, a); return (f32x4){(float)i[0], (float)i[1], (float)i[2], (float)i[3]}; }
;     __device__ __forceinline__ void operator()(const f32x4 (&acc)[2][2][4][2], const Unit& u, int wr, int wc, int fr, int fq) const {
;     ...
;             for (int m = 0; m < 4; ++m) { const int row_ = u.pm * BM + ai * HALF + wr * 64 + m * 16 + fr; rr[ai][m] = rs[row_]; pf[ai][m] = mode == 2 ? (float)pos[row_] : 0.f; }
; #pragma unroll
;         for (int ai = 0; ai < 2; ++ai)
; #pragma unroll
;             for (int m = 0; m < 4; ++m) {
;                 const int row = u.pm * BM + ai * HALF + wr * 64 + m * 16 + fr;
;                 const float r = rr[ai][m];
;                 f32x4 l0 = cvti4(acc[ai][0][m][0]) * r * s0a, l1 = cvti4(acc[ai][0][m][1]) * r * s0b, h0 = cvti4(acc[ai][1][m][0]) * r * s1a, h1 = cvti4(acc[ai][1][m][1]) * r * s1b;
;                 if (mode == 2) {
;                     float ss = (sq4(l0) + sq4(l1)) + (sq4(h0) + sq4(h1));
;                     ss += __shfl_xor(ss, 16); ss += __shfl_xor(ss, 32);
;                     const float rn = rsqrtf(ss * (1.f / 64.f) + EPS);
;                     l0 = l0 * rn * g0a; l1 = l1 * rn * g0b; h0 = h0 * rn * g1a; h1 = h1 * rn * g1b;
;                     f32x4 c0, c1, s0, s1; rope_cs(pf[ai][m], fr0, c0, s0); rope_cs(pf[ai][m], fr1, c1, s1);
;                     const f32x4 nl0 = l0 * c0 - h0 * s0, nh0 = h0 * c0 + l0 * s0, nl1 = l1 * c1 - h1 * s1, nh1 = h1 * c1 + l1 * s1;
;                     l0 = nl0 * scale; l1 = nl1 * scale; h0 = nh0 * scale; h1 = nh1 * scale;
.LBB0_791:
	s_waitcnt vmcnt(0)
	v_cvt_f32_i32_e32 v95, v95
	v_cvt_f32_i32_e32 v224, v224
	v_cvt_f32_i32_e32 v223, v223
	v_cvt_f32_i32_e32 v222, v222
	v_cvt_f32_i32_e32 v221, v221
	v_cvt_f32_i32_e32 v220, v220
	v_cvt_f32_i32_e32 v113, v113
	v_cvt_f32_i32_e32 v91, v91
	v_pk_mul_f32 v[196:197], v[94:95], v[196:197] op_sel_hi:[0,1]
	v_pk_mul_f32 v[200:201], v[94:95], v[200:201] op_sel_hi:[0,1]
	v_pk_mul_f32 v[198:199], v[94:95], v[198:199] op_sel_hi:[0,1]
	v_pk_mul_f32 v[194:195], v[94:95], v[194:195] op_sel_hi:[0,1]
	v_pk_mul_f32 v[218:219], v[32:33], v[196:197]
	v_pk_mul_f32 v[208:209], v[94:95], v[208:209] op_sel_hi:[0,1]
	v_pk_mul_f32 v[196:197], v[94:95], v[206:207] op_sel_hi:[0,1]
	v_pk_mul_f32 v[204:205], v[94:95], v[204:205] op_sel_hi:[0,1]
	v_pk_mul_f32 v[202:203], v[94:95], v[202:203] op_sel_hi:[0,1]
	s_mov_b32 s55, s54
	v_pk_mul_f32 v[198:199], v[38:39], v[198:199]
	v_pk_mul_f32 v[200:201], v[36:37], v[200:201]
	v_pk_mul_f32 v[194:195], v[34:35], v[194:195]
	v_pk_mul_f32 v[196:197], v[30:31], v[196:197]
	v_pk_mul_f32 v[206:207], v[28:29], v[208:209]
	v_pk_mul_f32 v[202:203], v[26:27], v[202:203]
	s_and_b64 vcc, exec, s[6:7]
	v_pk_mul_f32 v[204:205], v[24:25], v[204:205]
	s_cbranch_vccnz .LBB0_793
	v_mov_b32_e32 v226, v201
	v_mov_b32_e32 v227, v207
	v_mov_b32_e32 v208, v200
	v_mov_b32_e32 v209, v206
	v_pk_mul_f32 v[226:227], v[226:227], v[226:227]
	v_mov_b32_e32 v228, v199
	v_mov_b32_e32 v229, v197
	v_pk_fma_f32 v[208:209], v[208:209], v[208:209], v[226:227]
	v_mov_b32_e32 v226, v198
	v_mov_b32_e32 v227, v196
	v_pk_mul_f32 v[228:229], v[228:229], v[228:229]
	v_mov_b32_e32 v230, v195
	v_pk_fma_f32 v[226:227], v[226:227], v[226:227], v[228:229]
	v_mov_b32_e32 v228, v219
	v_mov_b32_e32 v229, v205
	v_pk_add_f32 v[208:209], v[208:209], v[226:227]
	v_mov_b32_e32 v226, v218
	v_mov_b32_e32 v227, v204
	v_pk_mul_f32 v[228:229], v[228:229], v[228:229]
	v_mov_b32_e32 v231, v203
	v_pk_fma_f32 v[226:227], v[226:227], v[226:227], v[228:229]
	v_mov_b32_e32 v228, v194
	v_mov_b32_e32 v229, v202
	v_pk_mul_f32 v[230:231], v[230:231], v[230:231]
	s_mov_b32 s0, s54
	v_pk_fma_f32 v[228:229], v[228:229], v[228:229], v[230:231]
	s_mov_b32 s1, s54
	v_pk_add_f32 v[226:227], v[226:227], v[228:229]
	s_nop 0
	v_pk_add_f32 v[208:209], v[208:209], v[226:227]
	s_nop 0
	v_add_f32_e32 v94, v208, v209
	v_and_b32_e32 v209, 64, v215
	v_xor_b32_e32 v208, 16, v215
	v_add_u32_e32 v209, 64, v209
	v_cmp_lt_i32_e32 vcc, v208, v209
	s_nop 1
	v_cndmask_b32_e32 v208, v215, v208, vcc
	v_lshlrev_b32_e32 v208, 2, v208
	ds_bpermute_b32 v208, v208, v94
	s_waitcnt lgkmcnt(0)
	v_add_f32_e32 v94, v94, v208
	v_xor_b32_e32 v208, 32, v215
	v_cmp_lt_i32_e32 vcc, v208, v209
	s_nop 1
	v_cndmask_b32_e32 v208, v215, v208, vcc
	v_lshlrev_b32_e32 v208, 2, v208
	ds_bpermute_b32 v208, v208, v94
	s_waitcnt lgkmcnt(0)
	v_add_f32_e32 v94, v94, v208
	v_fmamk_f32 v94, v94, 0x3c800000, v211
	v_mul_f32_e32 v208, 0x4b800000, v94
	v_cmp_gt_f32_e32 vcc, s84, v94
	s_nop 1
	v_cndmask_b32_e32 v94, v94, v208, vcc
	v_rsq_f32_e32 v94, v94
	s_nop 0
	v_mul_f32_e32 v208, 0x45800000, v94
	v_cndmask_b32_e32 v94, v94, v208, vcc
	v_pk_mul_f32 v[200:201], v[200:201], v[94:95] op_sel_hi:[1,0]
	v_pk_mul_f32 v[198:199], v[198:199], v[94:95] op_sel_hi:[1,0]
	v_pk_mul_f32 v[208:209], v[218:219], v[94:95] op_sel_hi:[1,0]
	v_pk_mul_f32 v[194:195], v[194:195], v[94:95] op_sel_hi:[1,0]
	v_pk_mul_f32 v[196:197], v[196:197], v[94:95] op_sel_hi:[1,0]
	v_pk_mul_f32 v[206:207], v[206:207], v[94:95] op_sel_hi:[1,0]
	v_pk_mul_f32 v[202:203], v[202:203], v[94:95] op_sel_hi:[1,0]
	v_pk_mul_f32 v[204:205], v[204:205], v[94:95] op_sel_hi:[1,0]
	v_mul_f32_e32 v94, v20, v95
	v_fract_f32_e32 v94, v94
	v_cos_f32_e32 v218, v94
	v_sin_f32_e32 v226, v94
	v_mul_f32_e32 v94, v21, v95
	v_fract_f32_e32 v94, v94
	v_cos_f32_e32 v219, v94
	v_sin_f32_e32 v227, v94
	v_mul_f32_e32 v94, v22, v95
	v_fract_f32_e32 v94, v94
	v_cos_f32_e32 v228, v94
	v_sin_f32_e32 v230, v94
	v_mul_f32_e32 v94, v23, v95
	v_fract_f32_e32 v94, v94
	v_cos_f32_e32 v229, v94
	v_sin_f32_e32 v231, v94
	v_mul_f32_e32 v94, v16, v95
	v_fract_f32_e32 v94, v94
	v_cos_f32_e32 v232, v94
	v_sin_f32_e32 v234, v94
	v_mul_f32_e32 v94, v17, v95
	v_fract_f32_e32 v94, v94
	v_cos_f32_e32 v233, v94
	v_sin_f32_e32 v235, v94
	v_mul_f32_e32 v94, v18, v95
	v_fract_f32_e32 v225, v94
	v_mul_f32_e32 v95, v19, v95
	v_cos_f32_e32 v94, v225
	v_sin_f32_e32 v236, v225
	v_fract_f32_e32 v225, v95
	v_sin_f32_e32 v237, v225
	v_pk_mul_f32 v[196:197], v[10:11], v[196:197]
	v_cos_f32_e32 v95, v225
	v_pk_mul_f32 v[198:199], v[14:15], v[198:199]
	v_pk_mul_f32 v[206:207], v[8:9], v[206:207]
	v_pk_mul_f32 v[238:239], v[230:231], v[196:197]
	v_pk_mul_f32 v[200:201], v[12:13], v[200:201]
	v_pk_mul_f32 v[202:203], v[2:3], v[202:203]
	v_pk_mul_f32 v[240:241], v[226:227], v[206:207]
	v_pk_fma_f32 v[238:239], v[228:229], v[198:199], v[238:239] neg_lo:[0,0,1] neg_hi:[0,0,1]
	v_pk_mul_f32 v[198:199], v[230:231], v[198:199]
	v_pk_mul_f32 v[194:195], v[6:7], v[194:195]
	v_pk_mul_f32 v[208:209], v[4:5], v[208:209]
	v_pk_mul_f32 v[204:205], v[0:1], v[204:205]
	v_pk_fma_f32 v[240:241], v[218:219], v[200:201], v[240:241] neg_lo:[0,0,1] neg_hi:[0,0,1]
	v_pk_mul_f32 v[200:201], v[226:227], v[200:201]
	v_pk_fma_f32 v[196:197], v[228:229], v[196:197], v[198:199]
	v_pk_mul_f32 v[198:199], v[236:237], v[202:203]
	v_pk_fma_f32 v[206:207], v[218:219], v[206:207], v[200:201]
	v_pk_mul_f32 v[200:201], v[234:235], v[204:205]
	v_pk_fma_f32 v[226:227], v[94:95], v[194:195], v[198:199] neg_lo:[0,0,1] neg_hi:[0,0,1]
	v_pk_mul_f32 v[194:195], v[236:237], v[194:195]
	v_pk_mul_f32 v[198:199], v[234:235], v[208:209]
	v_pk_fma_f32 v[218:219], v[232:233], v[208:209], v[200:201] neg_lo:[0,0,1] neg_hi:[0,0,1]
	v_pk_fma_f32 v[204:205], v[232:233], v[204:205], v[198:199]
	v_pk_fma_f32 v[94:95], v[94:95], v[202:203], v[194:195]
	v_pk_mul_f32 v[198:199], s[0:1], v[238:239]
	v_pk_mul_f32 v[200:201], s[54:55], v[240:241]
	v_pk_mul_f32 v[194:195], s[0:1], v[226:227]
	v_pk_mul_f32 v[218:219], s[54:55], v[218:219]
	v_pk_mul_f32 v[196:197], s[0:1], v[196:197]
	v_pk_mul_f32 v[206:207], s[54:55], v[206:207]
	v_pk_mul_f32 v[202:203], s[0:1], v[94:95]
	v_pk_mul_f32 v[204:205], s[54:55], v[204:205]

; __device__ __forceinline__ float sq4(const f32x4 v) { return (v[0] * v[0] + v[1] * v[1]) + (v[2] * v[2] + v[3] * v[3]); }
; __device__ __forceinline__ float rs16(const float* ss, int row) {
;     const f32x4 a = *(const f32x4*)(ss + (size_t)row * 4);
;     return rsqrtf(((a[0] + a[1]) + (a[2] + a[3])) * (1.f / 1024.f) + EPS);
; }
;     __device__ __forceinline__ void operator()(const f32x4 (&acc)[2][2][4][2], const Unit& u, int wr, int wc, int fr, int fq) const {
;     ...
; #pragma unroll
;         for (int ai = 0; ai < 2; ++ai)
; #pragma unroll
;             for (int m = 0; m < 4; ++m) {
;                 const int rt = ai * HALF + wr * 64 + m * 16 + fr; const float r = rs16(ss1, u.pm * BM + rt); rr[ai][m] = r;
;                 float ss = ((sq4(acc[ai][0][m][0]) + sq4(acc[ai][0][m][1])) + (sq4(acc[ai][1][m][0]) + sq4(acc[ai][1][m][1]))) * (r * r);
;                 ss += __shfl_xor(ss, 16); ss += __shfl_xor(ss, 32);
;                 if (fq == 0) xw[(ai * HALF + m * 16) * 4] = ss;
;             }
.LBB0_1767:
	v_lshl_add_u32 v152, s9, 8, v192
	v_mov_b32_e32 v248, v152
	v_ashrrev_i32_e32 v249, 31, v248
	v_lshlrev_b64 v[248:249], 4, v[248:249]
	v_lshl_add_u64 v[250:251], s[18:19], 0, v[248:249]
	global_load_dwordx4 v[216:219], v[250:251], off
	v_or_b32_e32 v248, 16, v152
	v_ashrrev_i32_e32 v249, 31, v248
	v_lshlrev_b64 v[248:249], 4, v[248:249]
	v_lshl_add_u64 v[250:251], s[18:19], 0, v[248:249]
	global_load_dwordx4 v[220:223], v[250:251], off
	v_or_b32_e32 v248, 32, v152
	v_ashrrev_i32_e32 v249, 31, v248
	v_lshlrev_b64 v[248:249], 4, v[248:249]
	v_lshl_add_u64 v[250:251], s[18:19], 0, v[248:249]
	global_load_dwordx4 v[224:227], v[250:251], off
	v_or_b32_e32 v248, 48, v152
	v_ashrrev_i32_e32 v249, 31, v248
	v_lshlrev_b64 v[248:249], 4, v[248:249]
	v_lshl_add_u64 v[250:251], s[18:19], 0, v[248:249]
	global_load_dwordx4 v[228:231], v[250:251], off
	v_add_u32_e32 v248, 0x80, v152
	v_ashrrev_i32_e32 v249, 31, v248
	v_lshlrev_b64 v[248:249], 4, v[248:249]
	v_lshl_add_u64 v[250:251], s[18:19], 0, v[248:249]
	global_load_dwordx4 v[232:235], v[250:251], off
	v_add_u32_e32 v248, 0x90, v152
	v_ashrrev_i32_e32 v249, 31, v248
	v_lshlrev_b64 v[248:249], 4, v[248:249]
	v_lshl_add_u64 v[250:251], s[18:19], 0, v[248:249]
	global_load_dwordx4 v[236:239], v[250:251], off
	v_add_u32_e32 v248, 0xa0, v152
	v_ashrrev_i32_e32 v249, 31, v248
	v_lshlrev_b64 v[248:249], 4, v[248:249]
	v_lshl_add_u64 v[250:251], s[18:19], 0, v[248:249]
	global_load_dwordx4 v[240:243], v[250:251], off
	v_add_u32_e32 v248, 0xb0, v152
	v_ashrrev_i32_e32 v249, 31, v248
	v_lshlrev_b64 v[248:249], 4, v[248:249]
	v_lshl_add_u64 v[250:251], s[18:19], 0, v[248:249]
	global_load_dwordx4 v[244:247], v[250:251], off
	s_waitcnt vmcnt(0)
	v_ashrrev_i32_e32 v153, 31, v152
	v_lshlrev_b64 v[144:145], 4, v[152:153]
	v_lshl_add_u64 v[146:147], s[18:19], 0, v[144:145]
	v_mov_b32_e32 v146, v216
	v_mov_b32_e32 v147, v217
	v_mov_b32_e32 v148, v218
	v_mov_b32_e32 v149, v219
	v_and_b32_e32 v151, 64, v199
	v_xor_b32_e32 v150, 16, v199
	v_add_u32_e32 v162, 64, v151
	v_cmp_lt_i32_e32 vcc, v150, v162
	v_mul_f32_e32 v154, v125, v125
	v_mul_f32_e32 v155, v127, v127
	v_cndmask_b32_e32 v163, v199, v150, vcc
	v_mul_f32_e32 v156, v121, v121
	v_mul_f32_e32 v157, v123, v123
	v_mul_f32_e32 v158, v117, v117
	v_mul_f32_e32 v159, v119, v119
	v_mul_f32_e32 v160, v113, v113
	v_mul_f32_e32 v161, v115, v115
	v_fmac_f32_e32 v154, v124, v124
	v_fmac_f32_e32 v155, v126, v126
	v_fmac_f32_e32 v156, v120, v120
	v_fmac_f32_e32 v157, v122, v122
	v_fmac_f32_e32 v158, v116, v116
	v_fmac_f32_e32 v159, v118, v118
	v_fmac_f32_e32 v160, v112, v112
	v_fmac_f32_e32 v161, v114, v114
	v_add_f32_e32 v154, v154, v155
	v_add_f32_e32 v155, v156, v157
	v_add_f32_e32 v156, v158, v159
	v_add_f32_e32 v157, v160, v161
	v_lshlrev_b32_e32 v201, 2, v163
	v_mov_b32_e32 v150, v147
	v_mov_b32_e32 v151, v148
	v_mov_b32_e32 v147, v149
	v_pk_add_f32 v[146:147], v[150:151], v[146:147]
	v_add_f32_e32 v148, v156, v157
	v_add_f32_e32 v146, v146, v147
	v_fmamk_f32 v146, v146, 0x3a800000, v200
	v_mul_f32_e32 v147, 0x4b800000, v146
	v_cmp_gt_f32_e32 vcc, s69, v146
	s_nop 1
	v_cndmask_b32_e32 v146, v146, v147, vcc
	v_rsq_f32_e32 v146, v146
	v_add_f32_e32 v147, v154, v155
	v_add_f32_e32 v147, v147, v148
	v_mul_f32_e32 v149, 0x45800000, v146
	v_cndmask_b32_e32 v176, v146, v149, vcc
	v_mul_f32_e32 v148, v176, v176
	v_mul_f32_e32 v146, v147, v148
	ds_bpermute_b32 v146, v201, v146
	v_xor_b32_e32 v149, 32, v199
	v_cmp_lt_i32_e32 vcc, v149, v162
	s_waitcnt lgkmcnt(0)
	v_fmac_f32_e32 v146, v147, v148
	v_cndmask_b32_e32 v149, v199, v149, vcc
	v_lshlrev_b32_e32 v202, 2, v149
	ds_bpermute_b32 v147, v202, v146
	s_and_saveexec_b64 s[0:1], s[2:3]
	s_cbranch_execz .LBB0_1769
	s_waitcnt lgkmcnt(0)
	v_add_f32_e32 v146, v146, v147
	ds_write_b32 v195, v146
.LBB0_1769:
	s_or_b64 exec, exec, s[0:1]
	v_or_b32_e32 v162, 16, v152
	v_ashrrev_i32_e32 v163, 31, v162
	s_waitcnt lgkmcnt(0)
	v_lshlrev_b64 v[146:147], 4, v[162:163]
	v_lshl_add_u64 v[148:149], s[18:19], 0, v[146:147]
	v_mov_b32_e32 v148, v220
	v_mov_b32_e32 v149, v221
	v_mov_b32_e32 v150, v222
	v_mov_b32_e32 v151, v223
	v_mul_f32_e32 v154, v109, v109
	v_mul_f32_e32 v155, v111, v111
	v_fmac_f32_e32 v154, v108, v108
	v_fmac_f32_e32 v155, v110, v110
	v_add_f32_e32 v164, v154, v155
	v_mul_f32_e32 v156, v105, v105
	v_mul_f32_e32 v157, v107, v107
	v_mul_f32_e32 v158, v101, v101
	v_mul_f32_e32 v159, v103, v103
	v_mul_f32_e32 v160, v97, v97
	v_mul_f32_e32 v161, v99, v99
	v_fmac_f32_e32 v156, v104, v104
	v_fmac_f32_e32 v157, v106, v106
	v_fmac_f32_e32 v158, v100, v100
	v_fmac_f32_e32 v159, v102, v102
	v_fmac_f32_e32 v160, v96, v96
	v_fmac_f32_e32 v161, v98, v98
	v_add_f32_e32 v156, v156, v157
	v_add_f32_e32 v157, v158, v159
	v_mov_b32_e32 v154, v149
	v_mov_b32_e32 v155, v150
	v_mov_b32_e32 v149, v151
	v_pk_add_f32 v[148:149], v[154:155], v[148:149]
	v_add_f32_e32 v150, v164, v156
	v_add_f32_e32 v148, v148, v149
	v_fmamk_f32 v148, v148, 0x3a800000, v200
	v_mul_f32_e32 v149, 0x4b800000, v148
	v_cmp_gt_f32_e32 vcc, s69, v148
	s_nop 1
	v_cndmask_b32_e32 v148, v148, v149, vcc
	v_rsq_f32_e32 v148, v148
	v_add_f32_e32 v149, v160, v161
	v_add_f32_e32 v149, v157, v149
	v_add_f32_e32 v149, v150, v149
	v_mul_f32_e32 v151, 0x45800000, v148
	v_cndmask_b32_e32 v203, v148, v151, vcc
	v_mul_f32_e32 v150, v203, v203
	v_mul_f32_e32 v148, v149, v150
	ds_bpermute_b32 v148, v201, v148
	s_waitcnt lgkmcnt(0)
	v_fmac_f32_e32 v148, v149, v150
	ds_bpermute_b32 v149, v202, v148
	s_and_saveexec_b64 s[0:1], s[2:3]
	s_cbranch_execz .LBB0_1771
	s_waitcnt lgkmcnt(0)
	v_add_f32_e32 v148, v148, v149
	ds_write_b32 v195, v148 offset:256
; __device__ __forceinline__ float sq4(const f32x4 v) { return (v[0] * v[0] + v[1] * v[1]) + (v[2] * v[2] + v[3] * v[3]); }
; __device__ __forceinline__ float rs16(const float* ss, int row) {
;     const f32x4 a = *(const f32x4*)(ss + (size_t)row * 4);
;     return rsqrtf(((a[0] + a[1]) + (a[2] + a[3])) * (1.f / 1024.f) + EPS);
; }
;     __device__ __forceinline__ void operator()(const f32x4 (&acc)[2][2][4][2], const Unit& u, int wr, int wc, int fr, int fq) const {
;     ...
; #pragma unroll
;         for (int ai = 0; ai < 2; ++ai)
; #pragma unroll
;             for (int m = 0; m < 4; ++m) {
;                 const int rt = ai * HALF + wr * 64 + m * 16 + fr; const float r = rs16(ss1, u.pm * BM + rt); rr[ai][m] = r;
;                 float ss = ((sq4(acc[ai][0][m][0]) + sq4(acc[ai][0][m][1])) + (sq4(acc[ai][1][m][0]) + sq4(acc[ai][1][m][1]))) * (r * r);
;                 ss += __shfl_xor(ss, 16); ss += __shfl_xor(ss, 32);
;                 if (fq == 0) xw[(ai * HALF + m * 16) * 4] = ss;
;             }
.LBB0_1771:
	s_or_b64 exec, exec, s[0:1]
	v_or_b32_e32 v164, 32, v152
	v_ashrrev_i32_e32 v165, 31, v164
	s_waitcnt lgkmcnt(0)
	v_lshlrev_b64 v[148:149], 4, v[164:165]
	v_lshl_add_u64 v[150:151], s[18:19], 0, v[148:149]
	v_mov_b32_e32 v154, v224
	v_mov_b32_e32 v155, v225
	v_mov_b32_e32 v156, v226
	v_mov_b32_e32 v157, v227
	v_mul_f32_e32 v150, v93, v93
	v_mul_f32_e32 v151, v95, v95
	v_fmac_f32_e32 v150, v92, v92
	v_fmac_f32_e32 v151, v94, v94
	v_add_f32_e32 v168, v150, v151
	v_mul_f32_e32 v158, v89, v89
	v_mul_f32_e32 v159, v91, v91
	v_mul_f32_e32 v160, v85, v85
	v_mul_f32_e32 v161, v87, v87
	v_mul_f32_e32 v166, v81, v81
	v_mul_f32_e32 v167, v83, v83
	v_fmac_f32_e32 v158, v88, v88
	v_fmac_f32_e32 v159, v90, v90
	v_fmac_f32_e32 v160, v84, v84
	v_fmac_f32_e32 v161, v86, v86
	v_fmac_f32_e32 v166, v80, v80
	v_fmac_f32_e32 v167, v82, v82
	v_add_f32_e32 v158, v158, v159
	v_add_f32_e32 v159, v160, v161
	v_mov_b32_e32 v150, v155
	v_mov_b32_e32 v151, v156
	v_mov_b32_e32 v155, v157
	v_pk_add_f32 v[150:151], v[150:151], v[154:155]
	v_add_f32_e32 v154, v168, v158
	v_add_f32_e32 v150, v150, v151
	v_fmamk_f32 v150, v150, 0x3a800000, v200
	v_mul_f32_e32 v151, 0x4b800000, v150
	v_cmp_gt_f32_e32 vcc, s69, v150
	s_nop 1
	v_cndmask_b32_e32 v150, v150, v151, vcc
	v_rsq_f32_e32 v150, v150
	v_add_f32_e32 v151, v166, v167
	v_add_f32_e32 v151, v159, v151
	v_add_f32_e32 v151, v154, v151
	v_mul_f32_e32 v155, 0x45800000, v150
	v_cndmask_b32_e32 v204, v150, v155, vcc
	v_mul_f32_e32 v154, v204, v204
	v_mul_f32_e32 v150, v151, v154
	ds_bpermute_b32 v150, v201, v150
	s_waitcnt lgkmcnt(0)
	v_fmac_f32_e32 v150, v151, v154
	ds_bpermute_b32 v151, v202, v150
	s_and_saveexec_b64 s[0:1], s[2:3]
	s_cbranch_execz .LBB0_1773
	s_waitcnt lgkmcnt(0)
	v_add_f32_e32 v150, v150, v151
	ds_write_b32 v195, v150 offset:512
.LBB0_1773:
	s_or_b64 exec, exec, s[0:1]
	v_or_b32_e32 v166, 48, v152
	v_ashrrev_i32_e32 v167, 31, v166
	s_waitcnt lgkmcnt(0)
	v_lshlrev_b64 v[150:151], 4, v[166:167]
	v_lshl_add_u64 v[154:155], s[18:19], 0, v[150:151]
	v_mov_b32_e32 v154, v228
	v_mov_b32_e32 v155, v229
	v_mov_b32_e32 v156, v230
	v_mov_b32_e32 v157, v231
	v_mul_f32_e32 v158, v77, v77
	v_mul_f32_e32 v159, v79, v79
	v_fmac_f32_e32 v158, v76, v76
	v_fmac_f32_e32 v159, v78, v78
	v_add_f32_e32 v172, v158, v159
	v_mul_f32_e32 v160, v73, v73
	v_mul_f32_e32 v161, v75, v75
	v_mul_f32_e32 v168, v69, v69
	v_mul_f32_e32 v169, v71, v71
	v_mul_f32_e32 v170, v65, v65
	v_mul_f32_e32 v171, v67, v67
	v_fmac_f32_e32 v160, v72, v72
	v_fmac_f32_e32 v161, v74, v74
	v_fmac_f32_e32 v168, v68, v68
	v_fmac_f32_e32 v169, v70, v70
	v_fmac_f32_e32 v170, v64, v64
	v_fmac_f32_e32 v171, v66, v66
	v_add_f32_e32 v160, v160, v161
	v_add_f32_e32 v161, v168, v169
	v_mov_b32_e32 v158, v155
	v_mov_b32_e32 v159, v156
	v_mov_b32_e32 v155, v157
	v_pk_add_f32 v[154:155], v[158:159], v[154:155]
	v_add_f32_e32 v156, v172, v160
	v_add_f32_e32 v154, v154, v155
	v_fmamk_f32 v154, v154, 0x3a800000, v200
	v_mul_f32_e32 v155, 0x4b800000, v154
	v_cmp_gt_f32_e32 vcc, s69, v154
	s_nop 1
	v_cndmask_b32_e32 v154, v154, v155, vcc
	v_rsq_f32_e32 v154, v154
	v_add_f32_e32 v155, v170, v171
	v_add_f32_e32 v155, v161, v155
	v_add_f32_e32 v155, v156, v155
	v_mul_f32_e32 v157, 0x45800000, v154
	v_cndmask_b32_e32 v205, v154, v157, vcc
	v_mul_f32_e32 v156, v205, v205
	v_mul_f32_e32 v154, v155, v156
	ds_bpermute_b32 v154, v201, v154
	s_waitcnt lgkmcnt(0)
	v_fmac_f32_e32 v154, v155, v156
	ds_bpermute_b32 v155, v202, v154
	s_and_saveexec_b64 s[0:1], s[2:3]
	s_cbranch_execz .LBB0_1775
	s_waitcnt lgkmcnt(0)
	v_add_f32_e32 v154, v154, v155
	ds_write_b32 v195, v154 offset:768
.LBB0_1775:
	s_or_b64 exec, exec, s[0:1]
	v_add_u32_e32 v168, 0x80, v152
	v_ashrrev_i32_e32 v169, 31, v168
	s_waitcnt lgkmcnt(0)
	v_lshlrev_b64 v[154:155], 4, v[168:169]
	v_lshl_add_u64 v[156:157], s[18:19], 0, v[154:155]
	v_mov_b32_e32 v156, v232
	v_mov_b32_e32 v157, v233
	v_mov_b32_e32 v158, v234
	v_mov_b32_e32 v159, v235
	v_mul_f32_e32 v160, v61, v61
	v_mul_f32_e32 v161, v63, v63
	v_fmac_f32_e32 v160, v60, v60
	v_fmac_f32_e32 v161, v62, v62
	v_add_f32_e32 v177, v160, v161
	v_mul_f32_e32 v170, v57, v57
	v_mul_f32_e32 v171, v59, v59
	v_mul_f32_e32 v172, v53, v53
	v_mul_f32_e32 v173, v55, v55
	v_mul_f32_e32 v174, v49, v49
	v_mul_f32_e32 v175, v51, v51
	v_fmac_f32_e32 v170, v56, v56
	v_fmac_f32_e32 v171, v58, v58
	v_fmac_f32_e32 v172, v52, v52
	v_fmac_f32_e32 v173, v54, v54
	v_fmac_f32_e32 v174, v48, v48
	v_fmac_f32_e32 v175, v50, v50
	v_add_f32_e32 v170, v170, v171
	v_add_f32_e32 v171, v172, v173
	v_mov_b32_e32 v160, v157
	v_mov_b32_e32 v161, v158
	v_mov_b32_e32 v157, v159
	v_pk_add_f32 v[156:157], v[160:161], v[156:157]
	v_add_f32_e32 v158, v177, v170
	v_add_f32_e32 v156, v156, v157
	v_fmamk_f32 v156, v156, 0x3a800000, v200
	v_mul_f32_e32 v157, 0x4b800000, v156
	v_cmp_gt_f32_e32 vcc, s69, v156
	s_nop 1
	v_cndmask_b32_e32 v156, v156, v157, vcc
	v_rsq_f32_e32 v156, v156
	v_add_f32_e32 v157, v174, v175
	v_add_f32_e32 v157, v171, v157
	v_add_f32_e32 v157, v158, v157
	v_mul_f32_e32 v159, 0x45800000, v156
	v_cndmask_b32_e32 v206, v156, v159, vcc
	v_mul_f32_e32 v158, v206, v206
	v_mul_f32_e32 v156, v157, v158
	ds_bpermute_b32 v156, v201, v156
	s_waitcnt lgkmcnt(0)
	v_fmac_f32_e32 v156, v157, v158
	ds_bpermute_b32 v157, v202, v156
	s_and_saveexec_b64 s[0:1], s[2:3]
	s_cbranch_execz .LBB0_1777
	s_waitcnt lgkmcnt(0)
	v_add_f32_e32 v156, v156, v157
	ds_write_b32 v195, v156 offset:2048
; __device__ __forceinline__ float sq4(const f32x4 v) { return (v[0] * v[0] + v[1] * v[1]) + (v[2] * v[2] + v[3] * v[3]); }
; __device__ __forceinline__ float rs16(const float* ss, int row) {
;     const f32x4 a = *(const f32x4*)(ss + (size_t)row * 4);
;     return rsqrtf(((a[0] + a[1]) + (a[2] + a[3])) * (1.f / 1024.f) + EPS);
; }
;     __device__ __forceinline__ void operator()(const f32x4 (&acc)[2][2][4][2], const Unit& u, int wr, int wc, int fr, int fq) const {
;     ...
; #pragma unroll
;         for (int ai = 0; ai < 2; ++ai)
; #pragma unroll
;             for (int m = 0; m < 4; ++m) {
;                 const int rt = ai * HALF + wr * 64 + m * 16 + fr; const float r = rs16(ss1, u.pm * BM + rt); rr[ai][m] = r;
;                 float ss = ((sq4(acc[ai][0][m][0]) + sq4(acc[ai][0][m][1])) + (sq4(acc[ai][1][m][0]) + sq4(acc[ai][1][m][1]))) * (r * r);
;                 ss += __shfl_xor(ss, 16); ss += __shfl_xor(ss, 32);
;                 if (fq == 0) xw[(ai * HALF + m * 16) * 4] = ss;
;             }
.LBB0_1777:
	s_or_b64 exec, exec, s[0:1]
	v_add_u32_e32 v170, 0x90, v152
	v_ashrrev_i32_e32 v171, 31, v170
	s_waitcnt lgkmcnt(0)
	v_lshlrev_b64 v[156:157], 4, v[170:171]
	v_lshl_add_u64 v[158:159], s[18:19], 0, v[156:157]
	v_mov_b32_e32 v158, v236
	v_mov_b32_e32 v159, v237
	v_mov_b32_e32 v160, v238
	v_mov_b32_e32 v161, v239
	v_mul_f32_e32 v172, v45, v45
	v_mul_f32_e32 v173, v47, v47
	v_fmac_f32_e32 v172, v44, v44
	v_fmac_f32_e32 v173, v46, v46
	v_add_f32_e32 v181, v172, v173
	v_mul_f32_e32 v174, v41, v41
	v_mul_f32_e32 v175, v43, v43
	v_mul_f32_e32 v177, v37, v37
	v_mul_f32_e32 v178, v39, v39
	v_mul_f32_e32 v179, v33, v33
	v_mul_f32_e32 v180, v35, v35
	v_fmac_f32_e32 v174, v40, v40
	v_fmac_f32_e32 v175, v42, v42
	v_fmac_f32_e32 v177, v36, v36
	v_fmac_f32_e32 v178, v38, v38
	v_fmac_f32_e32 v179, v32, v32
	v_fmac_f32_e32 v180, v34, v34
	v_add_f32_e32 v174, v174, v175
	v_add_f32_e32 v175, v177, v178
	v_mov_b32_e32 v172, v159
	v_mov_b32_e32 v173, v160
	v_mov_b32_e32 v159, v161
	v_pk_add_f32 v[158:159], v[172:173], v[158:159]
	v_add_f32_e32 v160, v181, v174
	v_add_f32_e32 v158, v158, v159
	v_fmamk_f32 v158, v158, 0x3a800000, v200
	v_mul_f32_e32 v159, 0x4b800000, v158
	v_cmp_gt_f32_e32 vcc, s69, v158
	s_nop 1
	v_cndmask_b32_e32 v158, v158, v159, vcc
	v_rsq_f32_e32 v158, v158
	v_add_f32_e32 v159, v179, v180
	v_add_f32_e32 v159, v175, v159
	v_add_f32_e32 v159, v160, v159
	v_mul_f32_e32 v161, 0x45800000, v158
	v_cndmask_b32_e32 v207, v158, v161, vcc
	v_mul_f32_e32 v160, v207, v207
	v_mul_f32_e32 v158, v159, v160
	ds_bpermute_b32 v158, v201, v158
	s_waitcnt lgkmcnt(0)
	v_fmac_f32_e32 v158, v159, v160
	ds_bpermute_b32 v159, v202, v158
	s_and_saveexec_b64 s[0:1], s[2:3]
	s_cbranch_execz .LBB0_1779
	s_waitcnt lgkmcnt(0)
	v_add_f32_e32 v158, v158, v159
	ds_write_b32 v195, v158 offset:2304
.LBB0_1779:
	s_or_b64 exec, exec, s[0:1]
	v_add_u32_e32 v172, 0xa0, v152
	v_ashrrev_i32_e32 v173, 31, v172
	s_waitcnt lgkmcnt(0)
	v_lshlrev_b64 v[158:159], 4, v[172:173]
	v_lshl_add_u64 v[160:161], s[18:19], 0, v[158:159]
	v_mov_b32_e32 v178, v240
	v_mov_b32_e32 v179, v241
	v_mov_b32_e32 v180, v242
	v_mov_b32_e32 v181, v243
	v_mul_f32_e32 v160, v29, v29
	v_mul_f32_e32 v161, v31, v31
	v_fmac_f32_e32 v160, v28, v28
	v_fmac_f32_e32 v161, v30, v30
	v_add_f32_e32 v185, v160, v161
	v_mul_f32_e32 v174, v25, v25
	v_mul_f32_e32 v175, v27, v27
	v_mul_f32_e32 v177, v21, v21
	v_mul_f32_e32 v182, v23, v23
	v_mul_f32_e32 v183, v17, v17
	v_mul_f32_e32 v184, v19, v19
	v_fmac_f32_e32 v174, v24, v24
	v_fmac_f32_e32 v175, v26, v26
	v_fmac_f32_e32 v177, v20, v20
	v_fmac_f32_e32 v182, v22, v22
	v_fmac_f32_e32 v183, v16, v16
	v_fmac_f32_e32 v184, v18, v18
	v_add_f32_e32 v174, v174, v175
	v_add_f32_e32 v175, v177, v182
	v_add_f32_e32 v174, v185, v174
	v_mov_b32_e32 v160, v179
	v_mov_b32_e32 v161, v180
	v_mov_b32_e32 v179, v181
	v_pk_add_f32 v[160:161], v[160:161], v[178:179]
	s_nop 0
	v_add_f32_e32 v160, v160, v161
	v_fmamk_f32 v160, v160, 0x3a800000, v200
	v_mul_f32_e32 v161, 0x4b800000, v160
	v_cmp_gt_f32_e32 vcc, s69, v160
	s_nop 1
	v_cndmask_b32_e32 v160, v160, v161, vcc
	v_rsq_f32_e32 v160, v160
	v_add_f32_e32 v161, v183, v184
	v_add_f32_e32 v161, v175, v161
	v_add_f32_e32 v161, v174, v161
	v_mul_f32_e32 v175, 0x45800000, v160
	v_cndmask_b32_e32 v208, v160, v175, vcc
	v_mul_f32_e32 v174, v208, v208
	v_mul_f32_e32 v160, v161, v174
	ds_bpermute_b32 v160, v201, v160
	s_waitcnt lgkmcnt(0)
	v_fmac_f32_e32 v160, v161, v174
	ds_bpermute_b32 v161, v202, v160
	s_and_saveexec_b64 s[0:1], s[2:3]
	s_cbranch_execz .LBB0_1781
	s_waitcnt lgkmcnt(0)
	v_add_f32_e32 v160, v160, v161
	ds_write_b32 v195, v160 offset:2560
.LBB0_1781:
	s_or_b64 exec, exec, s[0:1]
	v_add_u32_e32 v174, 0xb0, v152
	v_ashrrev_i32_e32 v175, 31, v174
	s_waitcnt lgkmcnt(0)
	v_lshlrev_b64 v[160:161], 4, v[174:175]
	v_lshl_add_u64 v[178:179], s[18:19], 0, v[160:161]
	v_mov_b32_e32 v178, v244
	v_mov_b32_e32 v179, v245
	v_mov_b32_e32 v180, v246
	v_mov_b32_e32 v181, v247
	v_mul_f32_e32 v177, v13, v13
	v_mul_f32_e32 v182, v15, v15
	v_mul_f32_e32 v183, v9, v9
	v_mul_f32_e32 v184, v11, v11
	v_fmac_f32_e32 v177, v12, v12
	v_fmac_f32_e32 v182, v14, v14
	v_fmac_f32_e32 v183, v8, v8
	v_fmac_f32_e32 v184, v10, v10
	v_add_f32_e32 v177, v177, v182
	v_add_f32_e32 v184, v183, v184
	v_mul_f32_e32 v185, v5, v5
	v_mul_f32_e32 v186, v7, v7
	v_mul_f32_e32 v187, v1, v1
	v_mul_f32_e32 v188, v3, v3
	v_fmac_f32_e32 v185, v4, v4
	v_fmac_f32_e32 v186, v6, v6
	v_fmac_f32_e32 v187, v0, v0
	v_fmac_f32_e32 v188, v2, v2
	v_add_f32_e32 v185, v185, v186
	v_add_f32_e32 v177, v177, v184
	v_mov_b32_e32 v182, v179
	v_mov_b32_e32 v183, v180
	v_mov_b32_e32 v179, v181
	v_pk_add_f32 v[178:179], v[182:183], v[178:179]
	s_nop 0
	v_add_f32_e32 v178, v178, v179
	v_fmamk_f32 v178, v178, 0x3a800000, v200
	v_mul_f32_e32 v179, 0x4b800000, v178
	v_cmp_gt_f32_e32 vcc, s69, v178
	s_nop 1
	v_cndmask_b32_e32 v178, v178, v179, vcc
	v_rsq_f32_e32 v178, v178
	v_add_f32_e32 v179, v187, v188
	v_add_f32_e32 v179, v185, v179
	v_mul_f32_e32 v180, 0x45800000, v178
	v_cndmask_b32_e32 v212, v178, v180, vcc
	v_add_f32_e32 v178, v177, v179
	v_mul_f32_e32 v179, v212, v212
	v_mul_f32_e32 v177, v178, v179
	ds_bpermute_b32 v177, v201, v177
	s_waitcnt lgkmcnt(0)
	v_fmac_f32_e32 v177, v178, v179
	ds_bpermute_b32 v178, v202, v177
	s_and_saveexec_b64 s[0:1], s[2:3]
	s_cbranch_execz .LBB0_1783
	s_waitcnt lgkmcnt(0)
	v_add_f32_e32 v177, v177, v178
	ds_write_b32 v195, v177 offset:2816
